# P1 converters: 4-bit table stores and w_out / peer_wq transpose stores written through (sc1): no dirty table lines in L2 beside the GEMM, less for the P3 barrier to write back
# baseline (speedup 1.0000x reference)
; __global__ void __launch_bounds__(NTHR, 2) k_main(Args a) {
;     ...
;         if (bid >= cfirst) for (int rr0 = ((bid - cfirst) * 8 + wave) * 4; rr0 < 2 * 16384; rr0 += (nb - cfirst) * 8 * 4) {
;             float4 v[4][4];
; #pragma unroll
;             for (int q = 0; q < 4; ++q) { const int rr = rr0 + q, which = rr >> 14, row = rr & 16383;
;                 typedef float f4v __attribute__((ext_vector_type(4))); const f4v* src4 = (const f4v*)((which ? a.peer_v : a.peer_u) + (size_t)row * D) + lane;
; #pragma unroll
;                 for (int jq = 0; jq < 4; ++jq) { const f4v t4 = __builtin_nontemporal_load(src4 + 64 * jq); v[q][jq] = make_float4(t4.x, t4.y, t4.z, t4.w); } }
; #pragma unroll
;             for (int q = 0; q < 4; ++q) { const int rr = rr0 + q, which = rr >> 14, row = rr & 16383;
;                 float ss = 0.f;
; #pragma unroll
;                 for (int jq = 0; jq < 4; ++jq) ss += v[q][jq].x * v[q][jq].x + v[q][jq].y * v[q][jq].y + v[q][jq].z * v[q][jq].z + v[q][jq].w * v[q][jq].w;
;                 ss = wave_sum(ss);
;                 const float step = ss > 0.f ? 0.335f * sqrtf(ss * (1.f / D)) : 1.f, inv = 1.f / step;
;                 unsigned short* dst = (unsigned short*)((which ? V8 : U8) + (size_t)row * 128) + lane;
; #pragma unroll
;                 for (int jq = 0; jq < 4; ++jq) { const float e4[4] = {v[q][jq].x, v[q][jq].y, v[q][jq].z, v[q][jq].w}; unsigned w4 = 0u;
; #pragma unroll
;                     for (int i = 0; i < 4; ++i) { const int qi = (int)fminf(fmaxf(floorf(e4[i] * inv), -8.f), 7.f); w4 |= ((unsigned)qi & 15u) << (4 * i); }
;                     dst[(size_t)jq * (16384 * 64)] = (unsigned short)w4; }
.LBB0_127:
	s_and_b32 s22, s11, 0x3ffc
	s_mov_b64 s[26:27], s[60:61]
	s_lshl_b32 s6, s22, 12
	v_readlane_b32 s60, v235, 16
	s_cmpk_lt_u32 s11, 0x4000
	v_readlane_b32 s74, v235, 30
	v_readlane_b32 s75, v235, 31
	s_cselect_b32 s1, s75, s85
	s_cselect_b32 s0, s74, s84
	v_lshl_add_u64 v[2:3], s[0:1], 0, v[64:65]
	v_lshl_add_u64 v[2:3], v[2:3], 0, s[6:7]
	global_load_dwordx4 v[72:75], v[2:3], off nt
	global_load_dwordx4 v[54:57], v[2:3], off offset:1024 nt
	global_load_dwordx4 v[50:53], v[2:3], off offset:2048 nt
	global_load_dwordx4 v[46:49], v[2:3], off offset:3072 nt
	v_readlane_b32 s8, v235, 36
	v_readlane_b32 s24, v235, 38
	v_add_co_u32_e32 v4, vcc, s13, v2
	s_cselect_b32 s1, s97, s51
	s_cselect_b32 s0, s96, s50
	s_cselect_b32 s24, 0, 4
	v_addc_co_u32_e32 v5, vcc, 0, v3, vcc
	v_lshl_add_u64 v[68:69], s[0:1], 0, v[66:67]
	v_add_co_u32_e32 v58, vcc, s14, v2
	global_load_dwordx4 v[42:45], v[4:5], off offset:1024 nt
	global_load_dwordx4 v[34:37], v[4:5], off offset:2048 nt
	v_addc_co_u32_e32 v59, vcc, 0, v3, vcc
	v_add_co_u32_e32 v2, vcc, s15, v2
	global_load_dwordx4 v[30:33], v[58:59], off nt
	global_load_dwordx4 v[26:29], v[58:59], off offset:1024 nt
	global_load_dwordx4 v[22:25], v[58:59], off offset:2048 nt
	global_load_dwordx4 v[18:21], v[58:59], off offset:3072 nt
	v_addc_co_u32_e32 v3, vcc, 0, v3, vcc
	v_readlane_b32 s9, v235, 37
	v_readlane_b32 s25, v235, 39
	s_or_b32 s8, s8, s24
	s_lshl_b32 s6, s22, 7
	v_lshl_add_u64 v[76:77], v[68:69], 0, s[6:7]
	v_readlane_b32 s61, v235, 17
	v_readlane_b32 s62, v235, 18
	v_readlane_b32 s63, v235, 19
	v_readlane_b32 s64, v235, 20
	v_readlane_b32 s65, v235, 21
	v_readlane_b32 s66, v235, 22
	v_readlane_b32 s67, v235, 23
	v_readlane_b32 s68, v235, 24
	v_readlane_b32 s69, v235, 25
	v_readlane_b32 s70, v235, 26
	v_readlane_b32 s71, v235, 27
	v_readlane_b32 s72, v235, 28
	v_readlane_b32 s73, v235, 29
	s_waitcnt vmcnt(9)
	v_mov_b32_e32 v8, v73
	s_waitcnt vmcnt(8)
	v_mov_b32_e32 v9, v55
	v_mov_b32_e32 v6, v72
	v_mov_b32_e32 v7, v54
	s_waitcnt vmcnt(7)
	v_mov_b32_e32 v16, v51
	s_waitcnt vmcnt(6)
	v_mov_b32_e32 v17, v47
	v_pk_mul_f32 v[8:9], v[8:9], v[8:9]
	v_mov_b32_e32 v10, v74
	v_mov_b32_e32 v11, v56
	v_mov_b32_e32 v14, v50
	v_mov_b32_e32 v15, v46
	v_pk_mul_f32 v[16:17], v[16:17], v[16:17]
	v_pk_fma_f32 v[6:7], v[6:7], v[6:7], v[8:9]
	v_mov_b32_e32 v12, v75
	v_mov_b32_e32 v13, v57
	v_mov_b32_e32 v38, v52
	v_mov_b32_e32 v39, v48
	v_pk_fma_f32 v[8:9], v[14:15], v[14:15], v[16:17]
	v_pk_fma_f32 v[6:7], v[10:11], v[10:11], v[6:7]
	v_mov_b32_e32 v40, v53
	v_mov_b32_e32 v41, v49
	v_pk_fma_f32 v[8:9], v[38:39], v[38:39], v[8:9]
	v_pk_fma_f32 v[6:7], v[12:13], v[12:13], v[6:7]
	v_pk_fma_f32 v[8:9], v[40:41], v[40:41], v[8:9]
	v_add_f32_e32 v6, v6, v7
	v_add_f32_e32 v6, v6, v8
	v_add_f32_e32 v6, v6, v9
	s_nop 1
	v_add_f32_dpp v6, v6, v6 quad_perm:[1,0,3,2] row_mask:0xf bank_mask:0xf bound_ctrl:1
	s_nop 1
	v_add_f32_dpp v6, v6, v6 quad_perm:[2,3,0,1] row_mask:0xf bank_mask:0xf bound_ctrl:1
	s_nop 1
	v_add_f32_dpp v6, v6, v6 row_half_mirror row_mask:0xf bank_mask:0xf bound_ctrl:1
	s_nop 1
	v_add_f32_dpp v6, v6, v6 row_mirror row_mask:0xf bank_mask:0xf bound_ctrl:1
	s_nop 0
	v_readlane_b32 s23, v6, 16
	v_readlane_b32 s24, v6, 48
	v_readlane_b32 s0, v6, 0
	v_readlane_b32 s1, v6, 32
	v_mov_b32_e32 v6, s23
	v_mov_b32_e32 v7, s24
	v_pk_add_f32 v[6:7], s[0:1], v[6:7]
	s_nop 0
	v_add_f32_e32 v60, v6, v7
	v_mul_f32_e32 v6, 0x3a800000, v60
	v_mul_f32_e32 v7, 0x4f800000, v6
	v_cmp_gt_f32_e32 vcc, s16, v6
	s_nop 1
	v_cndmask_b32_e32 v61, v6, v7, vcc
	v_sqrt_f32_e32 v71, v61
	global_load_dwordx4 v[38:41], v[4:5], off offset:3072 nt
	global_load_dwordx4 v[14:17], v[2:3], off nt
	global_load_dwordx4 v[10:13], v[2:3], off offset:1024 nt
	global_load_dwordx4 v[6:9], v[2:3], off offset:2048 nt
	v_add_u32_e32 v4, -1, v71
	v_add_u32_e32 v5, 1, v71
	v_fma_f32 v78, -v4, v71, v61
	v_fma_f32 v79, -v5, v71, v61
	v_cmp_ge_f32_e64 s[0:1], 0, v78
	s_nop 1
	v_cndmask_b32_e64 v4, v71, v4, s[0:1]
	v_cmp_lt_f32_e64 s[0:1], 0, v79
	s_nop 1
	v_cndmask_b32_e64 v4, v4, v5, s[0:1]
	v_mul_f32_e32 v5, 0x37800000, v4
	v_cndmask_b32_e32 v4, v4, v5, vcc
	v_cmp_class_f32_e32 vcc, v61, v63
	s_nop 1
	v_cndmask_b32_e32 v4, v4, v61, vcc
	v_mul_f32_e32 v4, 0x3eab851f, v4
	v_cmp_lt_f32_e32 vcc, 0, v60
	s_nop 1
	v_cndmask_b32_e32 v71, 1.0, v4, vcc
	global_load_dwordx4 v[58:61], v[58:59], off offset:-4096 nt
	s_nop 0
	global_load_dwordx4 v[2:5], v[2:3], off offset:3072 nt
	v_div_scale_f32 v78, s[0:1], v71, v71, 1.0
	v_rcp_f32_e32 v79, v78
	v_div_scale_f32 v80, vcc, 1.0, v71, 1.0
	v_fma_f32 v81, -v78, v79, 1.0
	v_fmac_f32_e32 v79, v81, v79
	v_mul_f32_e32 v81, v80, v79
	v_fma_f32 v82, -v78, v81, v80
	v_fmac_f32_e32 v81, v82, v79
	v_fma_f32 v78, -v78, v81, v80
	v_div_fmas_f32 v78, v78, v79, v81
	v_div_fixup_f32 v78, v78, v71, 1.0
	v_mul_f32_e32 v54, v78, v54
	v_mul_f32_e32 v55, v78, v55
	v_floor_f32_e32 v54, v54
	v_floor_f32_e32 v55, v55
	v_mul_f32_e32 v56, v78, v56
	v_med3_f32 v54, v54, s17, v70
	v_med3_f32 v55, v55, s17, v70
	v_floor_f32_e32 v56, v56
	v_cvt_i32_f32_e32 v54, v54
	v_cvt_i32_f32_e32 v55, v55
	v_med3_f32 v56, v56, s17, v70
	v_cvt_i32_f32_e32 v56, v56
	v_mul_f32_e32 v50, v78, v50
	v_and_b32_e32 v54, 15, v54
	v_lshlrev_b32_e32 v55, 4, v55
	v_floor_f32_e32 v50, v50
	v_mul_f32_e32 v57, v78, v57
	v_and_or_b32 v54, v55, s18, v54
	v_lshlrev_b32_e32 v55, 8, v56
	v_med3_f32 v50, v50, s17, v70
	v_floor_f32_e32 v57, v57
	v_and_or_b32 v54, v55, s19, v54
	v_cvt_i32_f32_e32 v55, v50
	v_mul_f32_e32 v50, v78, v51
	v_med3_f32 v57, v57, s17, v70
	v_floor_f32_e32 v50, v50
	v_mul_f32_e32 v52, v78, v52
	v_cvt_i32_f32_e32 v57, v57
	v_med3_f32 v50, v50, s17, v70
; __global__ void __launch_bounds__(NTHR, 2) k_main(Args a) {
;     ...
;             for (int q = 0; q < 4; ++q) { const int rr = rr0 + q, which = rr >> 14, row = rr & 16383;
;                 float ss = 0.f;
; #pragma unroll
;                 for (int jq = 0; jq < 4; ++jq) ss += v[q][jq].x * v[q][jq].x + v[q][jq].y * v[q][jq].y + v[q][jq].z * v[q][jq].z + v[q][jq].w * v[q][jq].w;
;                 ss = wave_sum(ss);
;                 const float step = ss > 0.f ? 0.335f * sqrtf(ss * (1.f / D)) : 1.f, inv = 1.f / step;
;                 unsigned short* dst = (unsigned short*)((which ? V8 : U8) + (size_t)row * 128) + lane;
; #pragma unroll
;                 for (int jq = 0; jq < 4; ++jq) { const float e4[4] = {v[q][jq].x, v[q][jq].y, v[q][jq].z, v[q][jq].w}; unsigned w4 = 0u;
; #pragma unroll
;                     for (int i = 0; i < 4; ++i) { const int qi = (int)fminf(fmaxf(floorf(e4[i] * inv), -8.f), 7.f); w4 |= ((unsigned)qi & 15u) << (4 * i); }
;                     dst[(size_t)jq * (16384 * 64)] = (unsigned short)w4; }
;                 if (lane == 0) (which ? SV : SU)[row] = 0.5f * step;
	v_floor_f32_e32 v52, v52
	v_cvt_i32_f32_e32 v56, v50
	v_med3_f32 v52, v52, s17, v70
	v_cvt_i32_f32_e32 v52, v52
	v_add_co_u32_e32 v50, vcc, s20, v76
	v_lshl_or_b32 v54, v57, 12, v54
	s_nop 0
	v_addc_co_u32_e32 v51, vcc, 0, v77, vcc
	v_mul_f32_e32 v46, v78, v46
	v_mov_b32_e32 v237, v54
	v_and_b32_e32 v50, 15, v55
	v_lshlrev_b32_e32 v51, 4, v56
	v_floor_f32_e32 v46, v46
	v_mul_f32_e32 v53, v78, v53
	v_and_or_b32 v50, v51, s18, v50
	v_lshlrev_b32_e32 v51, 8, v52
	v_med3_f32 v46, v46, s17, v70
	v_floor_f32_e32 v53, v53
	v_and_or_b32 v50, v51, s19, v50
	v_cvt_i32_f32_e32 v51, v46
	v_mul_f32_e32 v46, v78, v47
	v_mul_f32_e32 v72, v78, v72
	v_mul_f32_e32 v73, v78, v73
	v_med3_f32 v53, v53, s17, v70
	v_floor_f32_e32 v46, v46
	v_mul_f32_e32 v48, v78, v48
	v_mul_f32_e32 v74, v78, v74
	v_floor_f32_e32 v72, v72
	v_floor_f32_e32 v73, v73
	v_cvt_i32_f32_e32 v53, v53
	v_med3_f32 v46, v46, s17, v70
	v_floor_f32_e32 v48, v48
	v_floor_f32_e32 v74, v74
	v_med3_f32 v72, v72, s17, v70
	v_med3_f32 v73, v73, s17, v70
	v_cvt_i32_f32_e32 v52, v46
	v_med3_f32 v48, v48, s17, v70
	v_mul_f32_e32 v49, v78, v49
	v_mul_f32_e32 v75, v78, v75
	v_med3_f32 v74, v74, s17, v70
	v_cvt_i32_f32_e32 v72, v72
	v_cvt_i32_f32_e32 v73, v73
	v_cvt_i32_f32_e32 v48, v48
	v_floor_f32_e32 v49, v49
	v_floor_f32_e32 v75, v75
	v_cvt_i32_f32_e32 v74, v74
	v_add_co_u32_e32 v46, vcc, s21, v76
	v_med3_f32 v49, v49, s17, v70
	v_med3_f32 v75, v75, s17, v70
	v_lshl_or_b32 v50, v53, 12, v50
	v_addc_co_u32_e32 v47, vcc, 0, v77, vcc
	v_cvt_i32_f32_e32 v49, v49
	v_cvt_i32_f32_e32 v75, v75
	v_mov_b32_e32 v238, v50
	v_and_b32_e32 v46, 15, v51
	v_lshlrev_b32_e32 v47, 4, v52
	v_and_b32_e32 v72, 15, v72
	v_lshlrev_b32_e32 v73, 4, v73
	v_and_or_b32 v46, v47, s18, v46
	v_lshlrev_b32_e32 v47, 8, v48
	v_lshlrev_b32_e32 v74, 8, v74
	v_and_or_b32 v72, v73, s18, v72
	v_and_or_b32 v46, v47, s19, v46
	v_and_or_b32 v72, v74, s19, v72
	v_lshl_or_b32 v48, v49, 12, v46
	v_add_co_u32_e32 v46, vcc, 0x600000, v76
	v_lshl_or_b32 v72, v75, 12, v72
	s_nop 0
	v_addc_co_u32_e32 v47, vcc, 0, v77, vcc
	v_mov_b32_e32 v236, v72
	v_mov_b32_e32 v239, v48
	v_cndmask_b32_e64 v240, v237, v236, s[44:45]
	v_cndmask_b32_e64 v241, v239, v238, s[44:45]
	s_nop 1
	v_mov_b32_dpp v242, v240 quad_perm:[1,0,3,2] row_mask:0xf bank_mask:0xf
	v_mov_b32_dpp v243, v241 quad_perm:[1,0,3,2] row_mask:0xf bank_mask:0xf
	v_cndmask_b32_e64 v236, v236, v242, s[44:45]
	v_cndmask_b32_e64 v237, v242, v237, s[44:45]
	v_cndmask_b32_e64 v238, v238, v243, s[44:45]
	v_cndmask_b32_e64 v239, v243, v239, s[44:45]
	v_cndmask_b32_e64 v240, v238, v236, s[46:47]
	v_cndmask_b32_e64 v241, v239, v237, s[46:47]
	s_nop 1
	v_mov_b32_dpp v242, v240 quad_perm:[2,3,0,1] row_mask:0xf bank_mask:0xf
	v_mov_b32_dpp v243, v241 quad_perm:[2,3,0,1] row_mask:0xf bank_mask:0xf
	v_cndmask_b32_e64 v236, v236, v242, s[46:47]
	v_cndmask_b32_e64 v238, v242, v238, s[46:47]
	v_cndmask_b32_e64 v237, v237, v243, s[46:47]
	v_cndmask_b32_e64 v239, v243, v239, s[46:47]
	v_perm_b32 v248, v237, v236, s48
	v_perm_b32 v249, v239, v238, s48
	v_lshl_add_u64 v[246:247], v[76:77], 0, v[244:245]
	global_store_dwordx2 v[246:247], v[248:249], off sc1
	s_and_saveexec_b64 s[0:1], s[4:5]
	s_cbranch_execz .LBB0_129
	s_lshl_b32 s23, s22, 3
	v_mul_f32_e32 v46, 0.5, v71
	v_mov_b32_e32 v47, s23
	global_store_dword v47, v46, s[8:9]
.LBB0_129:
	s_or_b64 exec, exec, s[0:1]
	s_waitcnt vmcnt(2)
	v_mov_b32_e32 v48, v59
	v_mov_b32_e32 v49, v43
	v_mov_b32_e32 v46, v58
	v_mov_b32_e32 v47, v42
	v_pk_mul_f32 v[48:49], v[48:49], v[48:49]
	v_mov_b32_e32 v50, v60
	v_mov_b32_e32 v51, v44
	v_pk_fma_f32 v[46:47], v[46:47], v[46:47], v[48:49]
	v_mov_b32_e32 v52, v61
	v_pk_fma_f32 v[46:47], v[50:51], v[50:51], v[46:47]
	v_mov_b32_e32 v50, v35
	v_mov_b32_e32 v51, v39
	v_mov_b32_e32 v53, v45
	v_mov_b32_e32 v48, v34
	v_mov_b32_e32 v49, v38
	v_pk_mul_f32 v[50:51], v[50:51], v[50:51]
	v_pk_fma_f32 v[46:47], v[52:53], v[52:53], v[46:47]
	v_mov_b32_e32 v52, v36
	v_mov_b32_e32 v53, v40
	v_pk_fma_f32 v[48:49], v[48:49], v[48:49], v[50:51]
	v_mov_b32_e32 v54, v37
	v_mov_b32_e32 v55, v41
	v_pk_fma_f32 v[48:49], v[52:53], v[52:53], v[48:49]
	v_add_f32_e32 v46, v46, v47
	v_pk_fma_f32 v[48:49], v[54:55], v[54:55], v[48:49]
	s_nop 0
	v_add_f32_e32 v46, v46, v48
	v_add_f32_e32 v46, v46, v49
	s_nop 1
	v_add_f32_dpp v46, v46, v46 quad_perm:[1,0,3,2] row_mask:0xf bank_mask:0xf bound_ctrl:1
	s_nop 1
	v_add_f32_dpp v46, v46, v46 quad_perm:[2,3,0,1] row_mask:0xf bank_mask:0xf bound_ctrl:1
	s_nop 1
	v_add_f32_dpp v46, v46, v46 row_half_mirror row_mask:0xf bank_mask:0xf bound_ctrl:1
	s_nop 1
	v_add_f32_dpp v46, v46, v46 row_mirror row_mask:0xf bank_mask:0xf bound_ctrl:1
	s_nop 0
	v_readlane_b32 s23, v46, 16
	v_readlane_b32 s24, v46, 48
	v_readlane_b32 s0, v46, 0
	v_readlane_b32 s1, v46, 32
	v_mov_b32_e32 v46, s23
	v_mov_b32_e32 v47, s24
	v_pk_add_f32 v[46:47], s[0:1], v[46:47]
	s_nop 0
	v_add_f32_e32 v46, v46, v47
	v_mul_f32_e32 v47, 0x3a800000, v46
	v_mul_f32_e32 v48, 0x4f800000, v47
	v_cmp_gt_f32_e32 vcc, s16, v47
	s_nop 1
	v_cndmask_b32_e32 v47, v47, v48, vcc
	v_sqrt_f32_e32 v48, v47
	s_nop 0
	v_add_u32_e32 v49, -1, v48
	v_fma_f32 v50, -v49, v48, v47
	v_cmp_ge_f32_e64 s[0:1], 0, v50
	v_add_u32_e32 v50, 1, v48
	s_nop 0
	v_cndmask_b32_e64 v49, v48, v49, s[0:1]
	v_fma_f32 v48, -v50, v48, v47
	v_cmp_lt_f32_e64 s[0:1], 0, v48
	s_nop 1
	v_cndmask_b32_e64 v48, v49, v50, s[0:1]
	v_mul_f32_e32 v49, 0x37800000, v48
	v_cndmask_b32_e32 v48, v48, v49, vcc
	v_cmp_class_f32_e32 vcc, v47, v63
	s_nop 1
	v_cndmask_b32_e32 v47, v48, v47, vcc
	v_mul_f32_e32 v47, 0x3eab851f, v47
	v_cmp_lt_f32_e32 vcc, 0, v46
	s_nop 1
	v_cndmask_b32_e32 v46, 1.0, v47, vcc
	v_div_scale_f32 v47, s[0:1], v46, v46, 1.0
; __global__ void __launch_bounds__(NTHR, 2) k_main(Args a) {
;     ...
;             for (int q = 0; q < 4; ++q) { const int rr = rr0 + q, which = rr >> 14, row = rr & 16383;
;                 float ss = 0.f;
; #pragma unroll
;                 for (int jq = 0; jq < 4; ++jq) ss += v[q][jq].x * v[q][jq].x + v[q][jq].y * v[q][jq].y + v[q][jq].z * v[q][jq].z + v[q][jq].w * v[q][jq].w;
;                 ss = wave_sum(ss);
;                 const float step = ss > 0.f ? 0.335f * sqrtf(ss * (1.f / D)) : 1.f, inv = 1.f / step;
;                 unsigned short* dst = (unsigned short*)((which ? V8 : U8) + (size_t)row * 128) + lane;
; #pragma unroll
;                 for (int jq = 0; jq < 4; ++jq) { const float e4[4] = {v[q][jq].x, v[q][jq].y, v[q][jq].z, v[q][jq].w}; unsigned w4 = 0u;
; #pragma unroll
;                     for (int i = 0; i < 4; ++i) { const int qi = (int)fminf(fmaxf(floorf(e4[i] * inv), -8.f), 7.f); w4 |= ((unsigned)qi & 15u) << (4 * i); }
;                     dst[(size_t)jq * (16384 * 64)] = (unsigned short)w4; }
;                 if (lane == 0) (which ? SV : SU)[row] = 0.5f * step;
	v_rcp_f32_e32 v48, v47
	s_or_b32 s0, s6, 0x80
	s_mov_b32 s1, s7
	v_fma_f32 v49, -v47, v48, 1.0
	v_fmac_f32_e32 v48, v49, v48
	v_div_scale_f32 v49, vcc, 1.0, v46, 1.0
	v_mul_f32_e32 v50, v49, v48
	v_fma_f32 v51, -v47, v50, v49
	v_fmac_f32_e32 v50, v51, v48
	v_fma_f32 v47, -v47, v50, v49
	v_div_fmas_f32 v47, v47, v48, v50
	v_div_fixup_f32 v47, v47, v46, 1.0
	v_mul_f32_e32 v42, v47, v42
	v_mul_f32_e32 v43, v47, v43
	v_floor_f32_e32 v42, v42
	v_floor_f32_e32 v43, v43
	v_mul_f32_e32 v44, v47, v44
	v_med3_f32 v42, v42, s17, v70
	v_med3_f32 v43, v43, s17, v70
	v_floor_f32_e32 v44, v44
	v_cvt_i32_f32_e32 v42, v42
	v_cvt_i32_f32_e32 v43, v43
	v_med3_f32 v44, v44, s17, v70
	v_cvt_i32_f32_e32 v44, v44
	v_mul_f32_e32 v34, v47, v34
	v_and_b32_e32 v42, 15, v42
	v_lshlrev_b32_e32 v43, 4, v43
	v_floor_f32_e32 v34, v34
	v_mul_f32_e32 v45, v47, v45
	v_and_or_b32 v42, v43, s18, v42
	v_lshlrev_b32_e32 v43, 8, v44
	v_med3_f32 v34, v34, s17, v70
	v_floor_f32_e32 v45, v45
	v_and_or_b32 v42, v43, s19, v42
	v_cvt_i32_f32_e32 v43, v34
	v_mul_f32_e32 v34, v47, v35
	v_med3_f32 v45, v45, s17, v70
	v_floor_f32_e32 v34, v34
	v_mul_f32_e32 v36, v47, v36
	v_cvt_i32_f32_e32 v45, v45
	v_med3_f32 v34, v34, s17, v70
	v_floor_f32_e32 v36, v36
	v_cvt_i32_f32_e32 v44, v34
	v_med3_f32 v36, v36, s17, v70
	v_mul_f32_e32 v37, v47, v37
	v_lshl_add_u64 v[48:49], v[68:69], 0, s[0:1]
	v_cvt_i32_f32_e32 v36, v36
	v_floor_f32_e32 v37, v37
	v_add_co_u32_e32 v34, vcc, s20, v48
	v_med3_f32 v37, v37, s17, v70
	v_lshl_or_b32 v42, v45, 12, v42
	v_addc_co_u32_e32 v35, vcc, 0, v49, vcc
	v_cvt_i32_f32_e32 v37, v37
	v_mov_b32_e32 v237, v42
	v_and_b32_e32 v34, 15, v43
	v_lshlrev_b32_e32 v35, 4, v44
	v_and_or_b32 v34, v35, s18, v34
	v_lshlrev_b32_e32 v35, 8, v36
	v_and_or_b32 v34, v35, s19, v34
	v_lshl_or_b32 v36, v37, 12, v34
	v_mul_f32_e32 v34, v47, v38
	v_floor_f32_e32 v34, v34
	v_mul_f32_e32 v50, v47, v58
	v_mul_f32_e32 v51, v47, v59
	v_med3_f32 v34, v34, s17, v70
	v_floor_f32_e32 v50, v50
	v_floor_f32_e32 v51, v51
	v_mul_f32_e32 v52, v47, v60
	v_cvt_i32_f32_e32 v37, v34
	v_mul_f32_e32 v34, v47, v39
	v_med3_f32 v50, v50, s17, v70
	v_med3_f32 v51, v51, s17, v70
	v_floor_f32_e32 v52, v52
	v_floor_f32_e32 v34, v34
	v_cvt_i32_f32_e32 v50, v50
	v_cvt_i32_f32_e32 v51, v51
	v_med3_f32 v52, v52, s17, v70
	v_med3_f32 v34, v34, s17, v70
	v_cvt_i32_f32_e32 v52, v52
	v_cvt_i32_f32_e32 v38, v34
	v_add_co_u32_e32 v34, vcc, s21, v48
	v_and_b32_e32 v50, 15, v50
	s_nop 0
	v_addc_co_u32_e32 v35, vcc, 0, v49, vcc
	v_mov_b32_e32 v238, v36
	v_mul_f32_e32 v36, v47, v40
	v_lshlrev_b32_e32 v51, 4, v51
	v_floor_f32_e32 v36, v36
	v_and_or_b32 v50, v51, s18, v50
	v_lshlrev_b32_e32 v51, 8, v52
	v_and_b32_e32 v34, 15, v37
	v_med3_f32 v36, v36, s17, v70
	v_mul_f32_e32 v37, v47, v41
	v_and_or_b32 v50, v51, s19, v50
	v_mul_f32_e32 v51, v47, v61
	v_cvt_i32_f32_e32 v36, v36
	v_floor_f32_e32 v37, v37
	v_floor_f32_e32 v51, v51
	v_med3_f32 v37, v37, s17, v70
	v_med3_f32 v51, v51, s17, v70
	v_cvt_i32_f32_e32 v37, v37
	v_cvt_i32_f32_e32 v51, v51
	v_lshlrev_b32_e32 v35, 4, v38
	v_and_or_b32 v34, v35, s18, v34
	v_lshlrev_b32_e32 v35, 8, v36
	v_and_or_b32 v34, v35, s19, v34
	v_lshl_or_b32 v36, v37, 12, v34
	v_add_co_u32_e32 v34, vcc, 0x600000, v48
	v_lshl_or_b32 v50, v51, 12, v50
	s_nop 0
	v_addc_co_u32_e32 v35, vcc, 0, v49, vcc
	v_mov_b32_e32 v236, v50
	v_mov_b32_e32 v239, v36
	v_cndmask_b32_e64 v240, v237, v236, s[44:45]
	v_cndmask_b32_e64 v241, v239, v238, s[44:45]
	s_nop 1
	v_mov_b32_dpp v242, v240 quad_perm:[1,0,3,2] row_mask:0xf bank_mask:0xf
	v_mov_b32_dpp v243, v241 quad_perm:[1,0,3,2] row_mask:0xf bank_mask:0xf
	v_cndmask_b32_e64 v236, v236, v242, s[44:45]
	v_cndmask_b32_e64 v237, v242, v237, s[44:45]
	v_cndmask_b32_e64 v238, v238, v243, s[44:45]
	v_cndmask_b32_e64 v239, v243, v239, s[44:45]
	v_cndmask_b32_e64 v240, v238, v236, s[46:47]
	v_cndmask_b32_e64 v241, v239, v237, s[46:47]
	s_nop 1
	v_mov_b32_dpp v242, v240 quad_perm:[2,3,0,1] row_mask:0xf bank_mask:0xf
	v_mov_b32_dpp v243, v241 quad_perm:[2,3,0,1] row_mask:0xf bank_mask:0xf
	v_cndmask_b32_e64 v236, v236, v242, s[46:47]
	v_cndmask_b32_e64 v238, v242, v238, s[46:47]
	v_cndmask_b32_e64 v237, v237, v243, s[46:47]
	v_cndmask_b32_e64 v239, v243, v239, s[46:47]
	v_perm_b32 v248, v237, v236, s48
	v_perm_b32 v249, v239, v238, s48
	v_lshl_add_u64 v[246:247], v[48:49], 0, v[244:245]
	global_store_dwordx2 v[246:247], v[248:249], off sc1
	s_and_saveexec_b64 s[0:1], s[4:5]
	s_cbranch_execz .LBB0_131
	s_lshl_b32 s23, s22, 3
	v_mul_f32_e32 v34, 0.5, v46
	v_mov_b32_e32 v35, s23
	global_store_dword v35, v34, s[8:9] offset:8
; __global__ void __launch_bounds__(NTHR, 2) k_main(Args a) {
;     ...
;             for (int q = 0; q < 4; ++q) { const int rr = rr0 + q, which = rr >> 14, row = rr & 16383;
;                 float ss = 0.f;
; #pragma unroll
;                 for (int jq = 0; jq < 4; ++jq) ss += v[q][jq].x * v[q][jq].x + v[q][jq].y * v[q][jq].y + v[q][jq].z * v[q][jq].z + v[q][jq].w * v[q][jq].w;
;                 ss = wave_sum(ss);
;                 const float step = ss > 0.f ? 0.335f * sqrtf(ss * (1.f / D)) : 1.f, inv = 1.f / step;
;                 unsigned short* dst = (unsigned short*)((which ? V8 : U8) + (size_t)row * 128) + lane;
; #pragma unroll
;                 for (int jq = 0; jq < 4; ++jq) { const float e4[4] = {v[q][jq].x, v[q][jq].y, v[q][jq].z, v[q][jq].w}; unsigned w4 = 0u;
; #pragma unroll
;                     for (int i = 0; i < 4; ++i) { const int qi = (int)fminf(fmaxf(floorf(e4[i] * inv), -8.f), 7.f); w4 |= ((unsigned)qi & 15u) << (4 * i); }
;                     dst[(size_t)jq * (16384 * 64)] = (unsigned short)w4; }
;                 if (lane == 0) (which ? SV : SU)[row] = 0.5f * step;
.LBB0_131:
	s_or_b64 exec, exec, s[0:1]
	v_mov_b32_e32 v36, v31
	v_mov_b32_e32 v37, v27
	v_mov_b32_e32 v34, v30
	v_mov_b32_e32 v35, v26
	v_pk_mul_f32 v[36:37], v[36:37], v[36:37]
	v_mov_b32_e32 v38, v32
	v_mov_b32_e32 v39, v28
	v_pk_fma_f32 v[34:35], v[34:35], v[34:35], v[36:37]
	v_mov_b32_e32 v40, v33
	v_pk_fma_f32 v[34:35], v[38:39], v[38:39], v[34:35]
	v_mov_b32_e32 v38, v23
	v_mov_b32_e32 v39, v19
	v_mov_b32_e32 v41, v29
	v_mov_b32_e32 v36, v22
	v_mov_b32_e32 v37, v18
	v_pk_mul_f32 v[38:39], v[38:39], v[38:39]
	v_pk_fma_f32 v[34:35], v[40:41], v[40:41], v[34:35]
	v_mov_b32_e32 v40, v24
	v_mov_b32_e32 v41, v20
	v_pk_fma_f32 v[36:37], v[36:37], v[36:37], v[38:39]
	v_mov_b32_e32 v42, v25
	v_mov_b32_e32 v43, v21
	v_pk_fma_f32 v[36:37], v[40:41], v[40:41], v[36:37]
	v_add_f32_e32 v34, v34, v35
	v_pk_fma_f32 v[36:37], v[42:43], v[42:43], v[36:37]
	s_nop 0
	v_add_f32_e32 v34, v34, v36
	v_add_f32_e32 v34, v34, v37
	s_nop 1
	v_add_f32_dpp v34, v34, v34 quad_perm:[1,0,3,2] row_mask:0xf bank_mask:0xf bound_ctrl:1
	s_nop 1
	v_add_f32_dpp v34, v34, v34 quad_perm:[2,3,0,1] row_mask:0xf bank_mask:0xf bound_ctrl:1
	s_nop 1
	v_add_f32_dpp v34, v34, v34 row_half_mirror row_mask:0xf bank_mask:0xf bound_ctrl:1
	s_nop 1
	v_add_f32_dpp v34, v34, v34 row_mirror row_mask:0xf bank_mask:0xf bound_ctrl:1
	s_nop 0
	v_readlane_b32 s23, v34, 16
	v_readlane_b32 s24, v34, 48
	v_readlane_b32 s0, v34, 0
	v_readlane_b32 s1, v34, 32
	v_mov_b32_e32 v34, s23
	v_mov_b32_e32 v35, s24
	v_pk_add_f32 v[34:35], s[0:1], v[34:35]
	s_nop 0
	v_add_f32_e32 v34, v34, v35
	v_mul_f32_e32 v35, 0x3a800000, v34
	v_mul_f32_e32 v36, 0x4f800000, v35
	v_cmp_gt_f32_e32 vcc, s16, v35
	s_nop 1
	v_cndmask_b32_e32 v35, v35, v36, vcc
	v_sqrt_f32_e32 v36, v35
	s_nop 0
	v_add_u32_e32 v37, -1, v36
	v_fma_f32 v38, -v37, v36, v35
	v_cmp_ge_f32_e64 s[0:1], 0, v38
	v_add_u32_e32 v38, 1, v36
	s_nop 0
	v_cndmask_b32_e64 v37, v36, v37, s[0:1]
	v_fma_f32 v36, -v38, v36, v35
	v_cmp_lt_f32_e64 s[0:1], 0, v36
	s_nop 1
	v_cndmask_b32_e64 v36, v37, v38, s[0:1]
	v_mul_f32_e32 v37, 0x37800000, v36
	v_cndmask_b32_e32 v36, v36, v37, vcc
	v_cmp_class_f32_e32 vcc, v35, v63
	s_nop 1
	v_cndmask_b32_e32 v35, v36, v35, vcc
	v_mul_f32_e32 v35, 0x3eab851f, v35
	v_cmp_lt_f32_e32 vcc, 0, v34
	s_nop 1
	v_cndmask_b32_e32 v34, 1.0, v35, vcc
	v_div_scale_f32 v35, s[0:1], v34, v34, 1.0
	v_rcp_f32_e32 v36, v35
	s_or_b32 s0, s6, 0x100
	s_mov_b32 s1, s7
	v_fma_f32 v37, -v35, v36, 1.0
	v_fmac_f32_e32 v36, v37, v36
	v_div_scale_f32 v37, vcc, 1.0, v34, 1.0
	v_mul_f32_e32 v38, v37, v36
	v_fma_f32 v39, -v35, v38, v37
	v_fmac_f32_e32 v38, v39, v36
	v_fma_f32 v35, -v35, v38, v37
	v_div_fmas_f32 v35, v35, v36, v38
	v_div_fixup_f32 v35, v35, v34, 1.0
	v_mul_f32_e32 v26, v35, v26
	v_mul_f32_e32 v27, v35, v27
	v_floor_f32_e32 v26, v26
	v_floor_f32_e32 v27, v27
	v_mul_f32_e32 v28, v35, v28
	v_med3_f32 v26, v26, s17, v70
	v_med3_f32 v27, v27, s17, v70
	v_floor_f32_e32 v28, v28
	v_cvt_i32_f32_e32 v26, v26
	v_cvt_i32_f32_e32 v27, v27
	v_med3_f32 v28, v28, s17, v70
	v_cvt_i32_f32_e32 v28, v28
	v_mul_f32_e32 v22, v35, v22
	v_and_b32_e32 v26, 15, v26
	v_lshlrev_b32_e32 v27, 4, v27
	v_floor_f32_e32 v22, v22
	v_mul_f32_e32 v29, v35, v29
	v_and_or_b32 v26, v27, s18, v26
	v_lshlrev_b32_e32 v27, 8, v28
	v_med3_f32 v22, v22, s17, v70
	v_floor_f32_e32 v29, v29
	v_and_or_b32 v26, v27, s19, v26
	v_cvt_i32_f32_e32 v27, v22
	v_mul_f32_e32 v22, v35, v23
	v_med3_f32 v29, v29, s17, v70
	v_floor_f32_e32 v22, v22
	v_mul_f32_e32 v24, v35, v24
	v_cvt_i32_f32_e32 v29, v29
	v_med3_f32 v22, v22, s17, v70
	v_floor_f32_e32 v24, v24
	v_cvt_i32_f32_e32 v28, v22
	v_med3_f32 v24, v24, s17, v70
	v_lshl_add_u64 v[36:37], v[68:69], 0, s[0:1]
	v_mul_f32_e32 v30, v35, v30
	v_mul_f32_e32 v31, v35, v31
	v_cvt_i32_f32_e32 v24, v24
	v_floor_f32_e32 v30, v30
	v_floor_f32_e32 v31, v31
	v_mul_f32_e32 v32, v35, v32
	v_add_co_u32_e32 v22, vcc, s20, v36
	v_med3_f32 v30, v30, s17, v70
	v_med3_f32 v31, v31, s17, v70
	v_floor_f32_e32 v32, v32
	v_lshl_or_b32 v26, v29, 12, v26
	v_addc_co_u32_e32 v23, vcc, 0, v37, vcc
	v_mul_f32_e32 v18, v35, v18
	v_cvt_i32_f32_e32 v30, v30
	v_cvt_i32_f32_e32 v31, v31
	v_med3_f32 v32, v32, s17, v70
	v_mov_b32_e32 v237, v26
	v_and_b32_e32 v22, 15, v27
	v_lshlrev_b32_e32 v23, 4, v28
	v_floor_f32_e32 v18, v18
	v_cvt_i32_f32_e32 v32, v32
	v_mul_f32_e32 v25, v35, v25
	v_and_or_b32 v22, v23, s18, v22
	v_lshlrev_b32_e32 v23, 8, v24
	v_med3_f32 v18, v18, s17, v70
	v_floor_f32_e32 v25, v25
	v_and_or_b32 v22, v23, s19, v22
	v_cvt_i32_f32_e32 v23, v18
	v_mul_f32_e32 v18, v35, v19
	v_med3_f32 v25, v25, s17, v70
	v_floor_f32_e32 v18, v18
	v_mul_f32_e32 v20, v35, v20
	v_and_b32_e32 v30, 15, v30
	v_lshlrev_b32_e32 v31, 4, v31
	v_cvt_i32_f32_e32 v25, v25
	v_med3_f32 v18, v18, s17, v70
	v_floor_f32_e32 v20, v20
	v_and_or_b32 v30, v31, s18, v30
	v_lshlrev_b32_e32 v31, 8, v32
	v_cvt_i32_f32_e32 v24, v18
	v_med3_f32 v20, v20, s17, v70
	v_mul_f32_e32 v21, v35, v21
	v_and_or_b32 v30, v31, s19, v30
	v_mul_f32_e32 v31, v35, v33
	v_cvt_i32_f32_e32 v20, v20
	v_floor_f32_e32 v21, v21
	v_floor_f32_e32 v31, v31
	v_add_co_u32_e32 v18, vcc, s21, v36
	v_med3_f32 v21, v21, s17, v70
	v_med3_f32 v31, v31, s17, v70
	v_lshl_or_b32 v22, v25, 12, v22
	v_addc_co_u32_e32 v19, vcc, 0, v37, vcc
	v_cvt_i32_f32_e32 v21, v21
	v_cvt_i32_f32_e32 v31, v31
	v_mov_b32_e32 v238, v22
	v_and_b32_e32 v18, 15, v23
	v_lshlrev_b32_e32 v19, 4, v24
	v_and_or_b32 v18, v19, s18, v18
	v_lshlrev_b32_e32 v19, 8, v20
	v_and_or_b32 v18, v19, s19, v18
	v_lshl_or_b32 v20, v21, 12, v18
	v_add_co_u32_e32 v18, vcc, 0x600000, v36
	v_lshl_or_b32 v30, v31, 12, v30
	s_nop 0
	v_addc_co_u32_e32 v19, vcc, 0, v37, vcc
	v_mov_b32_e32 v236, v30
	v_mov_b32_e32 v239, v20
	v_cndmask_b32_e64 v240, v237, v236, s[44:45]
	v_cndmask_b32_e64 v241, v239, v238, s[44:45]
	s_nop 1
	v_mov_b32_dpp v242, v240 quad_perm:[1,0,3,2] row_mask:0xf bank_mask:0xf
	v_mov_b32_dpp v243, v241 quad_perm:[1,0,3,2] row_mask:0xf bank_mask:0xf
	v_cndmask_b32_e64 v236, v236, v242, s[44:45]
	v_cndmask_b32_e64 v237, v242, v237, s[44:45]
	v_cndmask_b32_e64 v238, v238, v243, s[44:45]
	v_cndmask_b32_e64 v239, v243, v239, s[44:45]
	v_cndmask_b32_e64 v240, v238, v236, s[46:47]
	v_cndmask_b32_e64 v241, v239, v237, s[46:47]
	s_nop 1
	v_mov_b32_dpp v242, v240 quad_perm:[2,3,0,1] row_mask:0xf bank_mask:0xf
	v_mov_b32_dpp v243, v241 quad_perm:[2,3,0,1] row_mask:0xf bank_mask:0xf
	v_cndmask_b32_e64 v236, v236, v242, s[46:47]
	v_cndmask_b32_e64 v238, v242, v238, s[46:47]
	v_cndmask_b32_e64 v237, v237, v243, s[46:47]
	v_cndmask_b32_e64 v239, v243, v239, s[46:47]
	v_perm_b32 v248, v237, v236, s48
	v_perm_b32 v249, v239, v238, s48
	v_lshl_add_u64 v[246:247], v[36:37], 0, v[244:245]
	global_store_dwordx2 v[246:247], v[248:249], off sc1
	s_and_saveexec_b64 s[0:1], s[4:5]
	s_mov_b64 s[60:61], s[26:27]
	s_cbranch_execz .LBB0_133
	s_lshl_b32 s23, s22, 3
	v_mul_f32_e32 v18, 0.5, v34
	v_mov_b32_e32 v19, s23
	global_store_dword v19, v18, s[8:9] offset:16
; __global__ void __launch_bounds__(NTHR, 2) k_main(Args a) {
;     ...
;             for (int q = 0; q < 4; ++q) { const int rr = rr0 + q, which = rr >> 14, row = rr & 16383;
;                 float ss = 0.f;
; #pragma unroll
;                 for (int jq = 0; jq < 4; ++jq) ss += v[q][jq].x * v[q][jq].x + v[q][jq].y * v[q][jq].y + v[q][jq].z * v[q][jq].z + v[q][jq].w * v[q][jq].w;
;                 ss = wave_sum(ss);
;                 const float step = ss > 0.f ? 0.335f * sqrtf(ss * (1.f / D)) : 1.f, inv = 1.f / step;
;                 unsigned short* dst = (unsigned short*)((which ? V8 : U8) + (size_t)row * 128) + lane;
; #pragma unroll
;                 for (int jq = 0; jq < 4; ++jq) { const float e4[4] = {v[q][jq].x, v[q][jq].y, v[q][jq].z, v[q][jq].w}; unsigned w4 = 0u;
; #pragma unroll
;                     for (int i = 0; i < 4; ++i) { const int qi = (int)fminf(fmaxf(floorf(e4[i] * inv), -8.f), 7.f); w4 |= ((unsigned)qi & 15u) << (4 * i); }
;                     dst[(size_t)jq * (16384 * 64)] = (unsigned short)w4; }
;                 if (lane == 0) (which ? SV : SU)[row] = 0.5f * step;
.LBB0_133:
	s_or_b64 exec, exec, s[0:1]
	v_mov_b32_e32 v20, v15
	v_mov_b32_e32 v21, v11
	v_mov_b32_e32 v18, v14
	v_mov_b32_e32 v19, v10
	v_pk_mul_f32 v[20:21], v[20:21], v[20:21]
	v_mov_b32_e32 v22, v16
	v_mov_b32_e32 v23, v12
	v_pk_fma_f32 v[18:19], v[18:19], v[18:19], v[20:21]
	v_mov_b32_e32 v24, v17
	v_pk_fma_f32 v[18:19], v[22:23], v[22:23], v[18:19]
	v_mov_b32_e32 v22, v7
	s_waitcnt vmcnt(12)
	v_mov_b32_e32 v23, v3
	v_mov_b32_e32 v25, v13
	v_mov_b32_e32 v20, v6
	v_mov_b32_e32 v21, v2
	v_pk_mul_f32 v[22:23], v[22:23], v[22:23]
	v_pk_fma_f32 v[18:19], v[24:25], v[24:25], v[18:19]
	v_mov_b32_e32 v24, v8
	v_mov_b32_e32 v25, v4
	v_pk_fma_f32 v[20:21], v[20:21], v[20:21], v[22:23]
	v_mov_b32_e32 v26, v9
	v_mov_b32_e32 v27, v5
	v_pk_fma_f32 v[20:21], v[24:25], v[24:25], v[20:21]
	v_add_f32_e32 v18, v18, v19
	v_pk_fma_f32 v[20:21], v[26:27], v[26:27], v[20:21]
	s_or_b32 s6, s6, 0x180
	v_add_f32_e32 v18, v18, v20
	v_add_f32_e32 v18, v18, v21
	s_nop 1
	v_add_f32_dpp v18, v18, v18 quad_perm:[1,0,3,2] row_mask:0xf bank_mask:0xf bound_ctrl:1
	s_nop 1
	v_add_f32_dpp v18, v18, v18 quad_perm:[2,3,0,1] row_mask:0xf bank_mask:0xf bound_ctrl:1
	s_nop 1
	v_add_f32_dpp v18, v18, v18 row_half_mirror row_mask:0xf bank_mask:0xf bound_ctrl:1
	s_nop 1
	v_add_f32_dpp v18, v18, v18 row_mirror row_mask:0xf bank_mask:0xf bound_ctrl:1
	s_nop 0
	v_readlane_b32 s23, v18, 16
	v_readlane_b32 s24, v18, 48
	v_readlane_b32 s0, v18, 0
	v_readlane_b32 s1, v18, 32
	v_mov_b32_e32 v18, s23
	v_mov_b32_e32 v19, s24
	v_pk_add_f32 v[18:19], s[0:1], v[18:19]
	s_nop 0
	v_add_f32_e32 v18, v18, v19
	v_mul_f32_e32 v19, 0x3a800000, v18
	v_mul_f32_e32 v20, 0x4f800000, v19
	v_cmp_gt_f32_e32 vcc, s16, v19
	s_nop 1
	v_cndmask_b32_e32 v19, v19, v20, vcc
	v_sqrt_f32_e32 v20, v19
	s_nop 0
	v_add_u32_e32 v21, -1, v20
	v_fma_f32 v22, -v21, v20, v19
	v_cmp_ge_f32_e64 s[0:1], 0, v22
	v_add_u32_e32 v22, 1, v20
	s_nop 0
	v_cndmask_b32_e64 v21, v20, v21, s[0:1]
	v_fma_f32 v20, -v22, v20, v19
	v_cmp_lt_f32_e64 s[0:1], 0, v20
	s_nop 1
	v_cndmask_b32_e64 v20, v21, v22, s[0:1]
	v_mul_f32_e32 v21, 0x37800000, v20
	v_cndmask_b32_e32 v20, v20, v21, vcc
	v_cmp_class_f32_e32 vcc, v19, v63
	s_nop 1
	v_cndmask_b32_e32 v19, v20, v19, vcc
	v_mul_f32_e32 v19, 0x3eab851f, v19
	v_cmp_lt_f32_e32 vcc, 0, v18
	s_nop 1
	v_cndmask_b32_e32 v18, 1.0, v19, vcc
	v_div_scale_f32 v19, s[0:1], v18, v18, 1.0
	v_rcp_f32_e32 v20, v19
	s_nop 0
	v_fma_f32 v21, -v19, v20, 1.0
	v_fmac_f32_e32 v20, v21, v20
	v_div_scale_f32 v21, vcc, 1.0, v18, 1.0
	v_mul_f32_e32 v22, v21, v20
	v_fma_f32 v23, -v19, v22, v21
	v_fmac_f32_e32 v22, v23, v20
	v_fma_f32 v19, -v19, v22, v21
	v_div_fmas_f32 v19, v19, v20, v22
	v_div_fixup_f32 v19, v19, v18, 1.0
	v_mul_f32_e32 v10, v19, v10
	v_mul_f32_e32 v11, v19, v11
	v_floor_f32_e32 v10, v10
	v_floor_f32_e32 v11, v11
	v_mul_f32_e32 v12, v19, v12
	v_med3_f32 v10, v10, s17, v70
	v_med3_f32 v11, v11, s17, v70
	v_floor_f32_e32 v12, v12
	v_cvt_i32_f32_e32 v10, v10
	v_cvt_i32_f32_e32 v11, v11
	v_med3_f32 v12, v12, s17, v70
	v_cvt_i32_f32_e32 v12, v12
	v_mul_f32_e32 v6, v19, v6
	v_and_b32_e32 v10, 15, v10
	v_lshlrev_b32_e32 v11, 4, v11
	v_floor_f32_e32 v6, v6
	v_mul_f32_e32 v13, v19, v13
	v_and_or_b32 v10, v11, s18, v10
	v_lshlrev_b32_e32 v11, 8, v12
	v_med3_f32 v6, v6, s17, v70
	v_floor_f32_e32 v13, v13
	v_and_or_b32 v10, v11, s19, v10
	v_cvt_i32_f32_e32 v11, v6
	v_mul_f32_e32 v6, v19, v7
	v_med3_f32 v13, v13, s17, v70
	v_floor_f32_e32 v6, v6
	v_mul_f32_e32 v8, v19, v8
	v_cvt_i32_f32_e32 v13, v13
	v_med3_f32 v6, v6, s17, v70
	v_floor_f32_e32 v8, v8
	v_cvt_i32_f32_e32 v12, v6
	v_med3_f32 v8, v8, s17, v70
	v_lshl_add_u64 v[20:21], v[68:69], 0, s[6:7]
	v_mul_f32_e32 v14, v19, v14
	v_mul_f32_e32 v15, v19, v15
	v_cvt_i32_f32_e32 v8, v8
	v_floor_f32_e32 v14, v14
	v_floor_f32_e32 v15, v15
	v_mul_f32_e32 v16, v19, v16
	v_add_co_u32_e32 v6, vcc, s20, v20
	v_med3_f32 v14, v14, s17, v70
	v_med3_f32 v15, v15, s17, v70
	v_floor_f32_e32 v16, v16
	v_lshl_or_b32 v10, v13, 12, v10
	v_addc_co_u32_e32 v7, vcc, 0, v21, vcc
	v_mul_f32_e32 v2, v19, v2
	v_cvt_i32_f32_e32 v14, v14
	v_cvt_i32_f32_e32 v15, v15
	v_med3_f32 v16, v16, s17, v70
	v_mov_b32_e32 v237, v10
	v_and_b32_e32 v6, 15, v11
	v_lshlrev_b32_e32 v7, 4, v12
	v_floor_f32_e32 v2, v2
	v_cvt_i32_f32_e32 v16, v16
	v_mul_f32_e32 v9, v19, v9
	v_and_or_b32 v6, v7, s18, v6
	v_lshlrev_b32_e32 v7, 8, v8
	v_med3_f32 v2, v2, s17, v70
	v_floor_f32_e32 v9, v9
	v_and_or_b32 v6, v7, s19, v6
	v_cvt_i32_f32_e32 v7, v2
	v_mul_f32_e32 v2, v19, v3
	v_med3_f32 v9, v9, s17, v70
	v_floor_f32_e32 v2, v2
	v_mul_f32_e32 v4, v19, v4
	v_and_b32_e32 v14, 15, v14
	v_lshlrev_b32_e32 v15, 4, v15
	v_cvt_i32_f32_e32 v9, v9
	v_med3_f32 v2, v2, s17, v70
	v_floor_f32_e32 v4, v4
	v_and_or_b32 v14, v15, s18, v14
	v_lshlrev_b32_e32 v15, 8, v16
	v_cvt_i32_f32_e32 v8, v2
	v_med3_f32 v4, v4, s17, v70
	v_mul_f32_e32 v5, v19, v5
	v_and_or_b32 v14, v15, s19, v14
	v_mul_f32_e32 v15, v19, v17
	v_cvt_i32_f32_e32 v4, v4
	v_floor_f32_e32 v5, v5
	v_floor_f32_e32 v15, v15
	v_add_co_u32_e32 v2, vcc, s21, v20
	v_med3_f32 v5, v5, s17, v70
	v_med3_f32 v15, v15, s17, v70
	v_lshl_or_b32 v6, v9, 12, v6
	v_addc_co_u32_e32 v3, vcc, 0, v21, vcc
	v_cvt_i32_f32_e32 v5, v5
	v_cvt_i32_f32_e32 v15, v15
	v_mov_b32_e32 v238, v6
	v_and_b32_e32 v2, 15, v7
	v_lshlrev_b32_e32 v3, 4, v8
	v_and_or_b32 v2, v3, s18, v2
	v_lshlrev_b32_e32 v3, 8, v4
	v_and_or_b32 v2, v3, s19, v2
	v_lshl_or_b32 v4, v5, 12, v2
	v_add_co_u32_e32 v2, vcc, 0x600000, v20
	v_lshl_or_b32 v14, v15, 12, v14
	s_nop 0
	v_addc_co_u32_e32 v3, vcc, 0, v21, vcc
	v_mov_b32_e32 v236, v14
	v_mov_b32_e32 v239, v4
	v_cndmask_b32_e64 v240, v237, v236, s[44:45]
	v_cndmask_b32_e64 v241, v239, v238, s[44:45]
	s_nop 1
	v_mov_b32_dpp v242, v240 quad_perm:[1,0,3,2] row_mask:0xf bank_mask:0xf
	v_mov_b32_dpp v243, v241 quad_perm:[1,0,3,2] row_mask:0xf bank_mask:0xf
	v_cndmask_b32_e64 v236, v236, v242, s[44:45]
	v_cndmask_b32_e64 v237, v242, v237, s[44:45]
	v_cndmask_b32_e64 v238, v238, v243, s[44:45]
	v_cndmask_b32_e64 v239, v243, v239, s[44:45]
	v_cndmask_b32_e64 v240, v238, v236, s[46:47]
	v_cndmask_b32_e64 v241, v239, v237, s[46:47]
	s_nop 1
	v_mov_b32_dpp v242, v240 quad_perm:[2,3,0,1] row_mask:0xf bank_mask:0xf
	v_mov_b32_dpp v243, v241 quad_perm:[2,3,0,1] row_mask:0xf bank_mask:0xf
	v_cndmask_b32_e64 v236, v236, v242, s[46:47]
	v_cndmask_b32_e64 v238, v242, v238, s[46:47]
	v_cndmask_b32_e64 v237, v237, v243, s[46:47]
	v_cndmask_b32_e64 v239, v243, v239, s[46:47]
	v_perm_b32 v248, v237, v236, s48
	v_perm_b32 v249, v239, v238, s48
	v_lshl_add_u64 v[246:247], v[20:21], 0, v[244:245]
	global_store_dwordx2 v[246:247], v[248:249], off sc1
	s_and_saveexec_b64 s[0:1], s[4:5]
	s_cbranch_execz .LBB0_126
	s_lshl_b32 s6, s22, 3
	v_mul_f32_e32 v2, 0.5, v18
	v_mov_b32_e32 v3, s6
	global_store_dword v3, v2, s[8:9] offset:24
	s_branch .LBB0_126

; #define LAS __attribute__((address_space(3)))
; #define LDS_WAIT() asm volatile("s_waitcnt lgkmcnt(0)" ::: "memory")
; __device__ __forceinline__ void transpose_item(const float* W, int ldw, int K, bf16* WT, LAS float* scr, int kb, int nbk, int lane) {
;     const int k0 = 64 * kb, n0 = 32 * nbk;
; #pragma unroll 8
;     for (int i = 0; i < 32; ++i) { const int kk = 2 * i + (lane >> 5); scr[kk * 33 + (lane & 31)] = W[(size_t)(k0 + kk) * ldw + n0 + (lane & 31)]; }
;     LDS_WAIT();
.LBB0_141:
	s_lshl_b32 s10, s5, 1
	s_lshl_b32 s11, s0, 1
	v_or_b32_e32 v24, s11, v4
	s_add_i32 s12, s10, 4
	s_add_i32 s13, s11, 4
	s_add_i32 s14, s10, 8
	s_add_i32 s15, s11, 8
	s_add_i32 s16, s10, 12
	s_add_i32 s17, s11, 12
	s_add_i32 s18, s10, 16
	s_add_i32 s19, s11, 16
	s_add_i32 s20, s10, 20
	s_add_i32 s21, s11, 20
	s_add_i32 s22, s10, 24
	s_add_i32 s23, s11, 24
	s_add_i32 s24, s10, 28
	s_add_i32 s25, s11, 28
	v_or_b32_e32 v22, s10, v3
	v_ashrrev_i32_e32 v25, 31, v24
	v_or_b32_e32 v26, s12, v3
	v_or_b32_e32 v28, s13, v4
	v_or_b32_e32 v30, s14, v3
	v_or_b32_e32 v32, s15, v4
	v_or_b32_e32 v34, s16, v3
	v_or_b32_e32 v36, s17, v4
	v_or_b32_e32 v38, s18, v3
	v_or_b32_e32 v40, s19, v4
	v_or_b32_e32 v42, s20, v3
	v_or_b32_e32 v44, s21, v4
	v_or_b32_e32 v46, s22, v3
	v_or_b32_e32 v48, s23, v4
	v_or_b32_e32 v50, s24, v3
	v_or_b32_e32 v52, s25, v4
	v_ashrrev_i32_e32 v23, 31, v22
	v_lshlrev_b64 v[24:25], 12, v[24:25]
	v_ashrrev_i32_e32 v29, 31, v28
	v_ashrrev_i32_e32 v27, 31, v26
	v_ashrrev_i32_e32 v33, 31, v32
	v_ashrrev_i32_e32 v31, 31, v30
	v_ashrrev_i32_e32 v37, 31, v36
	v_ashrrev_i32_e32 v35, 31, v34
	v_ashrrev_i32_e32 v41, 31, v40
	v_ashrrev_i32_e32 v39, 31, v38
	v_ashrrev_i32_e32 v45, 31, v44
	v_ashrrev_i32_e32 v43, 31, v42
	v_ashrrev_i32_e32 v49, 31, v48
	v_ashrrev_i32_e32 v47, 31, v46
	v_ashrrev_i32_e32 v53, 31, v52
	v_ashrrev_i32_e32 v51, 31, v50
	v_lshlrev_b64 v[22:23], 12, v[22:23]
	v_lshl_add_u64 v[24:25], v[16:17], 0, v[24:25]
	v_lshlrev_b64 v[26:27], 12, v[26:27]
	v_lshlrev_b64 v[28:29], 12, v[28:29]
	v_lshlrev_b64 v[30:31], 12, v[30:31]
	v_lshlrev_b64 v[32:33], 12, v[32:33]
	v_lshlrev_b64 v[34:35], 12, v[34:35]
	v_lshlrev_b64 v[36:37], 12, v[36:37]
	v_lshlrev_b64 v[38:39], 12, v[38:39]
	v_lshlrev_b64 v[40:41], 12, v[40:41]
	v_lshlrev_b64 v[42:43], 12, v[42:43]
	v_lshlrev_b64 v[44:45], 12, v[44:45]
	v_lshlrev_b64 v[46:47], 12, v[46:47]
	v_lshlrev_b64 v[48:49], 12, v[48:49]
	v_lshlrev_b64 v[50:51], 12, v[50:51]
	v_lshlrev_b64 v[52:53], 12, v[52:53]
	v_lshl_add_u64 v[22:23], v[16:17], 0, v[22:23]
	v_lshl_add_u64 v[28:29], v[16:17], 0, v[28:29]
	v_lshl_add_u64 v[26:27], v[16:17], 0, v[26:27]
	v_lshl_add_u64 v[32:33], v[16:17], 0, v[32:33]
	v_lshl_add_u64 v[30:31], v[16:17], 0, v[30:31]
	v_lshl_add_u64 v[36:37], v[16:17], 0, v[36:37]
	v_lshl_add_u64 v[34:35], v[16:17], 0, v[34:35]
	v_lshl_add_u64 v[40:41], v[16:17], 0, v[40:41]
	v_lshl_add_u64 v[38:39], v[16:17], 0, v[38:39]
	v_lshl_add_u64 v[44:45], v[16:17], 0, v[44:45]
	v_lshl_add_u64 v[42:43], v[16:17], 0, v[42:43]
	v_lshl_add_u64 v[48:49], v[16:17], 0, v[48:49]
	v_lshl_add_u64 v[46:47], v[16:17], 0, v[46:47]
	v_lshl_add_u64 v[52:53], v[16:17], 0, v[52:53]
	v_lshl_add_u64 v[50:51], v[16:17], 0, v[50:51]
	global_load_dword v54, v[24:25], off
	global_load_dword v55, v[22:23], off
	global_load_dword v56, v[28:29], off
	global_load_dword v57, v[26:27], off
	global_load_dword v58, v[32:33], off
	global_load_dword v59, v[30:31], off
	global_load_dword v60, v[36:37], off
	global_load_dword v61, v[34:35], off
	global_load_dword v62, v[40:41], off
	global_load_dword v63, v[38:39], off
	global_load_dword v64, v[44:45], off
	global_load_dword v65, v[42:43], off
	global_load_dword v66, v[48:49], off
	global_load_dword v67, v[46:47], off
	global_load_dword v68, v[52:53], off
	global_load_dword v69, v[50:51], off
	v_or_b32_e32 v24, s10, v1
	v_or_b32_e32 v22, s11, v2
	s_add_i32 s0, s0, 16
	s_add_i32 s5, s5, 16
	s_add_i32 s7, s7, -16
	v_mad_u64_u32 v[22:23], s[10:11], v22, s9, v[8:9]
	v_mad_u64_u32 v[24:25], s[10:11], v24, s9, v[8:9]
	v_or_b32_e32 v23, s12, v1
	v_or_b32_e32 v25, s13, v2
	v_or_b32_e32 v32, s14, v1
	v_or_b32_e32 v30, s15, v2
	v_or_b32_e32 v36, s16, v1
	v_or_b32_e32 v34, s17, v2
	v_or_b32_e32 v40, s18, v1
	v_or_b32_e32 v38, s19, v2
	v_or_b32_e32 v44, s20, v1
	v_or_b32_e32 v42, s21, v2
	v_or_b32_e32 v48, s22, v1
	v_or_b32_e32 v46, s23, v2
	v_or_b32_e32 v52, s24, v1
	v_or_b32_e32 v50, s25, v2
	s_cmp_lg_u32 s7, 0
	v_mad_u64_u32 v[26:27], s[10:11], v25, s9, v[8:9]
	v_mad_u64_u32 v[28:29], s[10:11], v23, s9, v[8:9]
	v_mad_u64_u32 v[30:31], s[10:11], v30, s9, v[8:9]
	v_mad_u64_u32 v[32:33], s[10:11], v32, s9, v[8:9]
	v_mad_u64_u32 v[34:35], s[10:11], v34, s9, v[8:9]
	v_mad_u64_u32 v[36:37], s[10:11], v36, s9, v[8:9]
	v_mad_u64_u32 v[38:39], s[10:11], v38, s9, v[8:9]
	v_mad_u64_u32 v[40:41], s[10:11], v40, s9, v[8:9]
	v_mad_u64_u32 v[42:43], s[10:11], v42, s9, v[8:9]
	v_mad_u64_u32 v[44:45], s[10:11], v44, s9, v[8:9]
	v_mad_u64_u32 v[46:47], s[10:11], v46, s9, v[8:9]
	v_mad_u64_u32 v[48:49], s[10:11], v48, s9, v[8:9]
	v_mad_u64_u32 v[50:51], s[10:11], v50, s9, v[8:9]
	v_mad_u64_u32 v[52:53], s[10:11], v52, s9, v[8:9]
	s_waitcnt vmcnt(15)
	ds_write_b32 v22, v54
	s_waitcnt vmcnt(14)
	ds_write_b32 v24, v55
	s_waitcnt vmcnt(13)
	ds_write_b32 v26, v56
	s_waitcnt vmcnt(12)
	ds_write_b32 v28, v57
	s_waitcnt vmcnt(11)
	ds_write_b32 v30, v58
	s_waitcnt vmcnt(10)
	ds_write_b32 v32, v59
	s_waitcnt vmcnt(9)
	ds_write_b32 v34, v60
	s_waitcnt vmcnt(8)
	ds_write_b32 v36, v61
	s_waitcnt vmcnt(7)
	ds_write_b32 v38, v62
	s_waitcnt vmcnt(6)
	ds_write_b32 v40, v63
	s_waitcnt vmcnt(5)
	ds_write_b32 v42, v64
	s_waitcnt vmcnt(4)
	ds_write_b32 v44, v65
	s_waitcnt vmcnt(3)
	ds_write_b32 v46, v66
	s_waitcnt vmcnt(2)
	ds_write_b32 v48, v67
	s_waitcnt vmcnt(1)
	ds_write_b32 v50, v68
	s_waitcnt vmcnt(0)
	ds_write_b32 v52, v69
	s_cbranch_scc1 .LBB0_141
; #define LAS __attribute__((address_space(3)))
; #define LDS_WAIT() asm volatile("s_waitcnt lgkmcnt(0)" ::: "memory")
; __device__ __forceinline__ void transpose_item(const float* W, int ldw, int K, bf16* WT, LAS float* scr, int kb, int nbk, int lane) {
;     ...
;     const int c = lane & 7;
; #pragma unroll
;     for (int j = 0; j < 4; ++j) { const int n = (lane >> 3) + 8 * j; const LAS float* s = scr + (8 * c) * 33 + n;
;         v4u o; o.x = pk2(s[0 * 33], s[1 * 33]); o.y = pk2(s[2 * 33], s[3 * 33]); o.z = pk2(s[4 * 33], s[5 * 33]); o.w = pk2(s[6 * 33], s[7 * 33]);
;         *(v4u*)(WT + (size_t)(n0 + n) * K + k0 + 8 * c) = o; }
;     LDS_WAIT();
	s_waitcnt lgkmcnt(0)
	ds_read2_b32 v[16:17], v18 offset0:33 offset1:41
	ds_read2_b32 v[26:27], v18 offset1:8
	ds_read2_b32 v[28:29], v18 offset0:66 offset1:74
	ds_read2_b32 v[30:31], v18 offset0:99 offset1:107
	ds_read2_b32 v[32:33], v18 offset0:132 offset1:140
	ds_read2_b32 v[34:35], v18 offset0:165 offset1:173
	ds_read2_b32 v[36:37], v18 offset0:198 offset1:206
	ds_read2_b32 v[38:39], v18 offset0:231 offset1:239
	s_mov_b32 s5, s1
	v_or_b32_e32 v3, s6, v9
	v_lshl_add_u64 v[40:41], s[4:5], 1, v[10:11]
	v_lshlrev_b32_e32 v4, 11, v3
	s_waitcnt lgkmcnt(6)
	v_cvt_pk_bf16_f32 v22, v26, v16
	s_waitcnt lgkmcnt(4)
	v_cvt_pk_bf16_f32 v23, v28, v30
	s_waitcnt lgkmcnt(2)
	v_cvt_pk_bf16_f32 v24, v32, v34
	s_waitcnt lgkmcnt(0)
	v_cvt_pk_bf16_f32 v25, v36, v38
	v_lshl_add_u64 v[42:43], v[40:41], 0, v[4:5]
	global_store_dwordx4 v[42:43], v[22:25], off sc1
	v_or_b32_e32 v3, s6, v19
	v_lshlrev_b32_e32 v4, 11, v3
	v_cvt_pk_bf16_f32 v22, v27, v17
	v_cvt_pk_bf16_f32 v23, v29, v31
	v_cvt_pk_bf16_f32 v24, v33, v35
	v_cvt_pk_bf16_f32 v25, v37, v39
	ds_read2_b32 v[26:27], v18 offset0:49 offset1:57
	ds_read2_b32 v[28:29], v18 offset0:16 offset1:24
	ds_read2_b32 v[30:31], v18 offset0:82 offset1:90
	ds_read2_b32 v[32:33], v18 offset0:115 offset1:123
	ds_read2_b32 v[34:35], v18 offset0:148 offset1:156
	ds_read2_b32 v[36:37], v18 offset0:181 offset1:189
	ds_read2_b32 v[38:39], v18 offset0:214 offset1:222
	ds_read2_b32 v[42:43], v18 offset0:247 offset1:255
	v_or_b32_e32 v3, s6, v20
	v_lshl_add_u64 v[16:17], v[40:41], 0, v[4:5]
	v_lshlrev_b32_e32 v4, 11, v3
	v_or_b32_e32 v3, s6, v21
	global_store_dwordx4 v[16:17], v[22:25], off sc1
	v_lshl_add_u64 v[16:17], v[40:41], 0, v[4:5]
	v_lshlrev_b32_e32 v4, 11, v3
	s_waitcnt lgkmcnt(6)
	v_cvt_pk_bf16_f32 v22, v28, v26
	s_waitcnt lgkmcnt(4)
	v_cvt_pk_bf16_f32 v23, v30, v32
	s_waitcnt lgkmcnt(2)
	v_cvt_pk_bf16_f32 v24, v34, v36
	s_waitcnt lgkmcnt(0)
	v_cvt_pk_bf16_f32 v25, v38, v42
	global_store_dwordx4 v[16:17], v[22:25], off sc1
	v_lshl_add_u64 v[16:17], v[40:41], 0, v[4:5]
	s_nop 0
	v_cvt_pk_bf16_f32 v22, v29, v27
	v_cvt_pk_bf16_f32 v23, v31, v33
	v_cvt_pk_bf16_f32 v24, v35, v37
	v_cvt_pk_bf16_f32 v25, v39, v43
	global_store_dwordx4 v[16:17], v[22:25], off sc1
	s_waitcnt lgkmcnt(0)
	s_branch .LBB0_137

; #define LAS __attribute__((address_space(3)))
; #define LDS_WAIT() asm volatile("s_waitcnt lgkmcnt(0)" ::: "memory")
; __device__ __forceinline__ void transpose_item(const float* W, int ldw, int K, bf16* WT, LAS float* scr, int kb, int nbk, int lane) {
;     const int k0 = 64 * kb, n0 = 32 * nbk;
; #pragma unroll 8
;     for (int i = 0; i < 32; ++i) { const int kk = 2 * i + (lane >> 5); scr[kk * 33 + (lane & 31)] = W[(size_t)(k0 + kk) * ldw + n0 + (lane & 31)]; }
;     LDS_WAIT();
.LBB0_144:
	s_lshl_b32 s10, s0, 1
	s_lshl_b32 s11, s5, 1
	v_or_b32_e32 v24, s11, v4
	s_add_i32 s12, s10, 4
	s_add_i32 s13, s11, 4
	s_add_i32 s14, s10, 8
	s_add_i32 s15, s11, 8
	s_add_i32 s16, s10, 12
	s_add_i32 s17, s11, 12
	s_add_i32 s18, s10, 16
	s_add_i32 s19, s11, 16
	s_add_i32 s20, s10, 20
	s_add_i32 s21, s11, 20
	s_add_i32 s22, s10, 24
	s_add_i32 s23, s11, 24
	s_add_i32 s24, s10, 28
	s_add_i32 s25, s11, 28
	v_or_b32_e32 v22, s10, v3
	v_ashrrev_i32_e32 v25, 31, v24
	v_or_b32_e32 v26, s12, v3
	v_or_b32_e32 v28, s13, v4
	v_or_b32_e32 v30, s14, v3
	v_or_b32_e32 v32, s15, v4
	v_or_b32_e32 v34, s16, v3
	v_or_b32_e32 v36, s17, v4
	v_or_b32_e32 v38, s18, v3
	v_or_b32_e32 v40, s19, v4
	v_or_b32_e32 v42, s20, v3
	v_or_b32_e32 v44, s21, v4
	v_or_b32_e32 v46, s22, v3
	v_or_b32_e32 v48, s23, v4
	v_or_b32_e32 v50, s24, v3
	v_or_b32_e32 v52, s25, v4
	v_ashrrev_i32_e32 v23, 31, v22
	v_lshlrev_b64 v[24:25], 12, v[24:25]
	v_ashrrev_i32_e32 v29, 31, v28
	v_ashrrev_i32_e32 v27, 31, v26
	v_ashrrev_i32_e32 v33, 31, v32
	v_ashrrev_i32_e32 v31, 31, v30
	v_ashrrev_i32_e32 v37, 31, v36
	v_ashrrev_i32_e32 v35, 31, v34
	v_ashrrev_i32_e32 v41, 31, v40
	v_ashrrev_i32_e32 v39, 31, v38
	v_ashrrev_i32_e32 v45, 31, v44
	v_ashrrev_i32_e32 v43, 31, v42
	v_ashrrev_i32_e32 v49, 31, v48
	v_ashrrev_i32_e32 v47, 31, v46
	v_ashrrev_i32_e32 v53, 31, v52
	v_ashrrev_i32_e32 v51, 31, v50
	v_lshlrev_b64 v[22:23], 12, v[22:23]
	v_lshl_add_u64 v[24:25], v[16:17], 0, v[24:25]
	v_lshlrev_b64 v[26:27], 12, v[26:27]
	v_lshlrev_b64 v[28:29], 12, v[28:29]
	v_lshlrev_b64 v[30:31], 12, v[30:31]
	v_lshlrev_b64 v[32:33], 12, v[32:33]
	v_lshlrev_b64 v[34:35], 12, v[34:35]
	v_lshlrev_b64 v[36:37], 12, v[36:37]
	v_lshlrev_b64 v[38:39], 12, v[38:39]
	v_lshlrev_b64 v[40:41], 12, v[40:41]
	v_lshlrev_b64 v[42:43], 12, v[42:43]
	v_lshlrev_b64 v[44:45], 12, v[44:45]
	v_lshlrev_b64 v[46:47], 12, v[46:47]
	v_lshlrev_b64 v[48:49], 12, v[48:49]
	v_lshlrev_b64 v[50:51], 12, v[50:51]
	v_lshlrev_b64 v[52:53], 12, v[52:53]
	v_lshl_add_u64 v[22:23], v[16:17], 0, v[22:23]
	v_lshl_add_u64 v[28:29], v[16:17], 0, v[28:29]
	v_lshl_add_u64 v[26:27], v[16:17], 0, v[26:27]
	v_lshl_add_u64 v[32:33], v[16:17], 0, v[32:33]
	v_lshl_add_u64 v[30:31], v[16:17], 0, v[30:31]
	v_lshl_add_u64 v[36:37], v[16:17], 0, v[36:37]
	v_lshl_add_u64 v[34:35], v[16:17], 0, v[34:35]
	v_lshl_add_u64 v[40:41], v[16:17], 0, v[40:41]
	v_lshl_add_u64 v[38:39], v[16:17], 0, v[38:39]
	v_lshl_add_u64 v[44:45], v[16:17], 0, v[44:45]
	v_lshl_add_u64 v[42:43], v[16:17], 0, v[42:43]
	v_lshl_add_u64 v[48:49], v[16:17], 0, v[48:49]
	v_lshl_add_u64 v[46:47], v[16:17], 0, v[46:47]
	v_lshl_add_u64 v[52:53], v[16:17], 0, v[52:53]
	v_lshl_add_u64 v[50:51], v[16:17], 0, v[50:51]
	global_load_dword v54, v[24:25], off
	global_load_dword v55, v[22:23], off
	global_load_dword v56, v[28:29], off
	global_load_dword v57, v[26:27], off
	global_load_dword v58, v[32:33], off
	global_load_dword v59, v[30:31], off
	global_load_dword v60, v[36:37], off
	global_load_dword v61, v[34:35], off
	global_load_dword v62, v[40:41], off
	global_load_dword v63, v[38:39], off
	global_load_dword v64, v[44:45], off
	global_load_dword v65, v[42:43], off
	global_load_dword v66, v[48:49], off
	global_load_dword v67, v[46:47], off
	global_load_dword v68, v[52:53], off
	global_load_dword v69, v[50:51], off
	v_or_b32_e32 v24, s10, v1
	v_or_b32_e32 v22, s11, v2
	s_add_i32 s5, s5, 16
	s_add_i32 s0, s0, 16
	s_add_i32 s7, s7, -16
	v_mad_u64_u32 v[22:23], s[10:11], v22, s9, v[8:9]
	v_mad_u64_u32 v[24:25], s[10:11], v24, s9, v[8:9]
	v_or_b32_e32 v23, s12, v1
	v_or_b32_e32 v25, s13, v2
	v_or_b32_e32 v32, s14, v1
	v_or_b32_e32 v30, s15, v2
	v_or_b32_e32 v36, s16, v1
	v_or_b32_e32 v34, s17, v2
	v_or_b32_e32 v40, s18, v1
	v_or_b32_e32 v38, s19, v2
	v_or_b32_e32 v44, s20, v1
	v_or_b32_e32 v42, s21, v2
	v_or_b32_e32 v48, s22, v1
	v_or_b32_e32 v46, s23, v2
	v_or_b32_e32 v52, s24, v1
	v_or_b32_e32 v50, s25, v2
	s_cmp_lg_u32 s7, 0
	v_mad_u64_u32 v[26:27], s[10:11], v25, s9, v[8:9]
	v_mad_u64_u32 v[28:29], s[10:11], v23, s9, v[8:9]
	v_mad_u64_u32 v[30:31], s[10:11], v30, s9, v[8:9]
	v_mad_u64_u32 v[32:33], s[10:11], v32, s9, v[8:9]
	v_mad_u64_u32 v[34:35], s[10:11], v34, s9, v[8:9]
	v_mad_u64_u32 v[36:37], s[10:11], v36, s9, v[8:9]
	v_mad_u64_u32 v[38:39], s[10:11], v38, s9, v[8:9]
	v_mad_u64_u32 v[40:41], s[10:11], v40, s9, v[8:9]
	v_mad_u64_u32 v[42:43], s[10:11], v42, s9, v[8:9]
	v_mad_u64_u32 v[44:45], s[10:11], v44, s9, v[8:9]
	v_mad_u64_u32 v[46:47], s[10:11], v46, s9, v[8:9]
	v_mad_u64_u32 v[48:49], s[10:11], v48, s9, v[8:9]
	v_mad_u64_u32 v[50:51], s[10:11], v50, s9, v[8:9]
	v_mad_u64_u32 v[52:53], s[10:11], v52, s9, v[8:9]
	s_waitcnt vmcnt(15)
	ds_write_b32 v22, v54
	s_waitcnt vmcnt(14)
	ds_write_b32 v24, v55
	s_waitcnt vmcnt(13)
	ds_write_b32 v26, v56
	s_waitcnt vmcnt(12)
	ds_write_b32 v28, v57
	s_waitcnt vmcnt(11)
	ds_write_b32 v30, v58
	s_waitcnt vmcnt(10)
	ds_write_b32 v32, v59
	s_waitcnt vmcnt(9)
	ds_write_b32 v34, v60
	s_waitcnt vmcnt(8)
	ds_write_b32 v36, v61
	s_waitcnt vmcnt(7)
	ds_write_b32 v38, v62
	s_waitcnt vmcnt(6)
	ds_write_b32 v40, v63
	s_waitcnt vmcnt(5)
	ds_write_b32 v42, v64
	s_waitcnt vmcnt(4)
	ds_write_b32 v44, v65
	s_waitcnt vmcnt(3)
	ds_write_b32 v46, v66
	s_waitcnt vmcnt(2)
	ds_write_b32 v48, v67
	s_waitcnt vmcnt(1)
	ds_write_b32 v50, v68
	s_waitcnt vmcnt(0)
	ds_write_b32 v52, v69
	s_cbranch_scc1 .LBB0_144
; #define LAS __attribute__((address_space(3)))
; #define LDS_WAIT() asm volatile("s_waitcnt lgkmcnt(0)" ::: "memory")
; __device__ __forceinline__ void transpose_item(const float* W, int ldw, int K, bf16* WT, LAS float* scr, int kb, int nbk, int lane) {
;     ...
;     const int c = lane & 7;
; #pragma unroll
;     for (int j = 0; j < 4; ++j) { const int n = (lane >> 3) + 8 * j; const LAS float* s = scr + (8 * c) * 33 + n;
;         v4u o; o.x = pk2(s[0 * 33], s[1 * 33]); o.y = pk2(s[2 * 33], s[3 * 33]); o.z = pk2(s[4 * 33], s[5 * 33]); o.w = pk2(s[6 * 33], s[7 * 33]);
;         *(v4u*)(WT + (size_t)(n0 + n) * K + k0 + 8 * c) = o; }
;     LDS_WAIT();
	s_waitcnt lgkmcnt(0)
	ds_read2_b32 v[16:17], v18 offset0:33 offset1:41
	ds_read2_b32 v[26:27], v18 offset1:8
	ds_read2_b32 v[28:29], v18 offset0:66 offset1:74
	ds_read2_b32 v[30:31], v18 offset0:99 offset1:107
	ds_read2_b32 v[32:33], v18 offset0:132 offset1:140
	ds_read2_b32 v[34:35], v18 offset0:165 offset1:173
	ds_read2_b32 v[36:37], v18 offset0:198 offset1:206
	ds_read2_b32 v[38:39], v18 offset0:231 offset1:239
	v_or_b32_e32 v42, s4, v9
	s_ashr_i32 s7, s6, 31
	v_ashrrev_i32_e32 v43, 31, v42
	v_lshl_add_u64 v[40:41], s[6:7], 1, v[14:15]
	v_lshlrev_b64 v[42:43], 11, v[42:43]
	s_waitcnt lgkmcnt(6)
	v_cvt_pk_bf16_f32 v22, v26, v16
	s_waitcnt lgkmcnt(4)
	v_cvt_pk_bf16_f32 v23, v28, v30
	s_waitcnt lgkmcnt(2)
	v_cvt_pk_bf16_f32 v24, v32, v34
	s_waitcnt lgkmcnt(0)
	v_cvt_pk_bf16_f32 v25, v36, v38
	v_lshl_add_u64 v[42:43], v[40:41], 0, v[42:43]
	v_or_b32_e32 v16, s4, v19
	global_store_dwordx4 v[42:43], v[22:25], off sc1
	s_nop 1
	v_cvt_pk_bf16_f32 v22, v27, v17
	v_ashrrev_i32_e32 v17, 31, v16
	v_cvt_pk_bf16_f32 v23, v29, v31
	v_cvt_pk_bf16_f32 v24, v33, v35
	v_cvt_pk_bf16_f32 v25, v37, v39
	v_lshlrev_b64 v[16:17], 11, v[16:17]
	ds_read2_b32 v[26:27], v18 offset0:49 offset1:57
	ds_read2_b32 v[28:29], v18 offset0:16 offset1:24
	ds_read2_b32 v[30:31], v18 offset0:82 offset1:90
	ds_read2_b32 v[32:33], v18 offset0:115 offset1:123
	ds_read2_b32 v[34:35], v18 offset0:148 offset1:156
	ds_read2_b32 v[36:37], v18 offset0:181 offset1:189
	ds_read2_b32 v[38:39], v18 offset0:214 offset1:222
	ds_read2_b32 v[42:43], v18 offset0:247 offset1:255
	v_lshl_add_u64 v[16:17], v[40:41], 0, v[16:17]
	global_store_dwordx4 v[16:17], v[22:25], off sc1
	v_or_b32_e32 v16, s4, v20
	v_ashrrev_i32_e32 v17, 31, v16
	v_lshlrev_b64 v[16:17], 11, v[16:17]
	s_waitcnt lgkmcnt(6)
	v_cvt_pk_bf16_f32 v22, v28, v26
	s_waitcnt lgkmcnt(4)
	v_cvt_pk_bf16_f32 v23, v30, v32
	s_waitcnt lgkmcnt(2)
	v_cvt_pk_bf16_f32 v24, v34, v36
	s_waitcnt lgkmcnt(0)
	v_cvt_pk_bf16_f32 v25, v38, v42
	v_lshl_add_u64 v[16:17], v[40:41], 0, v[16:17]
	global_store_dwordx4 v[16:17], v[22:25], off sc1
	v_or_b32_e32 v16, s4, v21
	v_ashrrev_i32_e32 v17, 31, v16
	v_lshlrev_b64 v[16:17], 11, v[16:17]
	v_cvt_pk_bf16_f32 v22, v29, v27
	v_cvt_pk_bf16_f32 v23, v31, v33
	v_cvt_pk_bf16_f32 v24, v35, v37
	v_cvt_pk_bf16_f32 v25, v39, v43
	v_lshl_add_u64 v[16:17], v[40:41], 0, v[16:17]
	global_store_dwordx4 v[16:17], v[22:25], off sc1
	s_waitcnt lgkmcnt(0)
	s_branch .LBB0_137
